# deferred x conversion rebalanced: segment 0's idle tail converts segments 1 and 2, segment 1's converts segment 3
# baseline (speedup 1.0000x reference)
; __device__ __forceinline__ unsigned cvt_pk_bf16(float lo, float hi) { unsigned r; asm volatile("v_cvt_pk_bf16_f32 %0, %1, %2" : "=v"(r) : "v"(lo), "v"(hi)); return r; }
; #define GAS __attribute__((address_space(1)))
; __device__ __forceinline__ void phase_prep(const Params& P, unsigned char* smem) {
;     ...
;     GAS bf16* xb = (GAS bf16*)(ws + WS_XB); GAS float* rstd1 = (GAS float*)(ws + WS_RSTD1);
;     for (int rid = gw; rid < NSEG * RSB; rid += NGW) {
;         const int s = rid / RSB, lr = rid % RSB; const float* src = nullptr;
;         if (lr < RS) src = P.x + ((size_t)(lr / TSEG) * SEQ + (size_t)s * TSEG + (lr % TSEG)) * DM;
;         else if (s == 0) { if (lr >= RS + 48 && lr < RS + 64) src = P.meta + (size_t)(lr - RS - 48) * DM; }
;         else continue;
;         GAS v2u* o8 = (GAS v2u*)(xb + (size_t)rid * DM) + lane; float ss = 0.f;
;         if (src) { const f32x4* xr = (const f32x4*)src + lane;
; #pragma unroll
;             for (int j = 0; j < 8; ++j) { const f32x4 v = __builtin_nontemporal_load((const GAS f32x4*)xr + 64 * j); ss += (v[0] * v[0] + v[1] * v[1]) + (v[2] * v[2] + v[3] * v[3]); v2u o; o.x = cvt_pk_bf16(v[0], v[1]); o.y = cvt_pk_bf16(v[2], v[3]); o8[64 * j] = o; } }
.LBB0_693:
	v_readlane_b32 s0, v254, 38
	s_nop 3
	s_cmp_gt_u32 s0, 1
	s_cbranch_scc1 .Lxc_done
	s_cmp_lt_u32 s2, 0x60
	s_cbranch_scc1 .Lxc_done
	s_mov_b64 s[36:37], exec
	s_mov_b64 exec, -1
	s_cmp_eq_u32 s0, 0
	s_cselect_b32 s55, 2, 3
	s_cselect_b32 s0, 1, 3
	v_readfirstlane_b32 s1, v172
	v_readlane_b32 s16, v252, 8
	v_readlane_b32 s17, v252, 9
	s_lshr_b32 s1, s1, 6
	s_sub_i32 s9, s2, 0x60
	s_lshl_b32 s9, s9, 3
	s_add_i32 s9, s9, s1
	s_mov_b32 s56, s9
	s_sub_i32 s14, s82, 0x60
	s_lshl_b32 s14, s14, 3
.Lxc_seg:
	s_mov_b32 s9, s56
	s_lshl_b32 s15, s0, 12
	s_mul_i32 s23, s0, 0x2100
	s_add_u32 s48, s80, 0xb0c0000
	s_addc_u32 s49, s81, 0
	s_add_u32 s52, s80, 0x134c0000
	s_addc_u32 s53, s81, 0
	v_and_b32_e32 v31, 63, v172
	v_lshlrev_b32_e32 v28, 4, v31
	v_lshlrev_b32_e32 v30, 3, v31
	v_add_u32_e32 v29, 0x1000, v28
	v_mov_b32_e32 v31, 0
	v_mov_b32_e32 v32, 0x3a000000
	v_mov_b32_e32 v33, 0x358637bd
	s_cmp_lt_u32 s9, 0x2000
	s_cbranch_scc0 .Lxc_exit
	s_lshr_b32 s20, s9, 12
	s_and_b32 s22, s9, 0xfff
	s_lshl_b32 s20, s20, 14
	s_add_i32 s20, s20, s22
	s_add_i32 s20, s20, s15
	s_lshl_b32 s20, s20, 13
	s_add_u32 s40, s16, s20
	s_addc_u32 s41, s17, 0
	global_load_dwordx4 v[40:43], v28, s[40:41] nt
	global_load_dwordx4 v[44:47], v28, s[40:41] offset:1024 nt
	global_load_dwordx4 v[48:51], v28, s[40:41] offset:2048 nt
	global_load_dwordx4 v[52:55], v28, s[40:41] offset:3072 nt
	global_load_dwordx4 v[56:59], v29, s[40:41] nt
	global_load_dwordx4 v[60:63], v29, s[40:41] offset:1024 nt
	global_load_dwordx4 v[64:67], v29, s[40:41] offset:2048 nt
	global_load_dwordx4 v[68:71], v29, s[40:41] offset:3072 nt

; __device__ __forceinline__ unsigned cvt_pk_bf16(float lo, float hi) { unsigned r; asm volatile("v_cvt_pk_bf16_f32 %0, %1, %2" : "=v"(r) : "v"(lo), "v"(hi)); return r; }
; #define GAS __attribute__((address_space(1)))
; __device__ __forceinline__ void phase_prep(const Params& P, unsigned char* smem) {
;     ...
;     for (int rid = gw; rid < NSEG * RSB; rid += NGW) {
;         const int s = rid / RSB, lr = rid % RSB; const float* src = nullptr;
;         if (lr < RS) src = P.x + ((size_t)(lr / TSEG) * SEQ + (size_t)s * TSEG + (lr % TSEG)) * DM;
;         else if (s == 0) { if (lr >= RS + 48 && lr < RS + 64) src = P.meta + (size_t)(lr - RS - 48) * DM; }
;         else continue;
;         GAS v2u* o8 = (GAS v2u*)(xb + (size_t)rid * DM) + lane; float ss = 0.f;
;         if (src) { const f32x4* xr = (const f32x4*)src + lane;
; #pragma unroll
;             for (int j = 0; j < 8; ++j) { const f32x4 v = __builtin_nontemporal_load((const GAS f32x4*)xr + 64 * j); ss += (v[0] * v[0] + v[1] * v[1]) + (v[2] * v[2] + v[3] * v[3]); v2u o; o.x = cvt_pk_bf16(v[0], v[1]); o.y = cvt_pk_bf16(v[2], v[3]); o8[64 * j] = o; } }
;         else {
; #pragma unroll
;             for (int j = 0; j < 8; ++j) { v2u o; o.x = 0u; o.y = 0u; o8[64 * j] = o; } }
;         ss = wave_sum(ss);
;         if (lane == 0) rstd1[rid] = rsqrtf(ss * (1.f / DM) + EPS);
;     }
.Lxc_exit:
	s_add_i32 s0, s0, 1
	s_cmp_le_u32 s0, s55
	s_cbranch_scc1 .Lxc_seg
	s_mov_b64 exec, s[36:37]
